# q/k in-proj epilogue path: rowsq loads hoisted (7 per tile), per-group vmcnt(0) waits dropped
# speedup vs baseline: 1.0016x; 1.0016x over previous
;     __device__ __forceinline__ void operator()(const f32x4 (&acc)[2][2][4][2], const Unit& u, int wr, int wc, int fr, int fq) const {
;     ...
; #pragma unroll
;             for (int ai = 0; ai < 2; ++ai)
; #pragma unroll
;                 for (int m = 0; m < 4; ++m) {
;                     const int row = pm * 256 + ai * 128 + wr * 64 + m * 16 + fr;
;                     const float rinv = rsqrtf(rowsq[row] * (1.f / DM) + EPSN);
;                     int b, kidx, t = 0;
;                     if (isctx) { const int rc = row - MLAT; b = rc >> 8; kidx = rc & 255; } else { b = row >> 13; t = row & (SEQ - 1); kidx = CTXL + t; }
;                     f32x4 val[2][2]; float ss = 0.f;
; #pragma unroll
;                     for (int bj = 0; bj < 2; ++bj)
; #pragma unroll
;                         for (int n = 0; n < 2; ++n) { val[bj][n] = acc[ai][bj][m][n] * rinv + bv[bj][n]; const f32x4 q = val[bj][n]; ss += (q[0] * q[0] + q[1] * q[1]) + (q[2] * q[2] + q[3] * q[3]); }
;                     ss += __shfl_xor(ss, 16); ss += __shfl_xor(ss, 32);
;                     const float rn = rsqrtf(ss * (1.f / 64.f) + EPSN);
; #pragma unroll
;                     for (int bj = 0; bj < 2; ++bj) {
;                         f32x4 y0 = val[bj][0] * rn * gv[bj][0], y1 = val[bj][1] * rn * gv[bj][1];
;                         if (!isctx) {
;                             const int pos = bj == 0 ? (t >> 6) : (t & 63);
;                             const f32x4 r0 = *(const f32x4*)(rope + (size_t)(pos * 16 + 4 * fq) * 2);
;                             const f32x4 r1 = *(const f32x4*)(rope + (size_t)(pos * 16 + 4 * fq + 2) * 2);
;                             f32x4 z0, z1;
;                             z0[0] = y0[0] * r0[0] - y0[1] * r0[1]; z0[1] = y0[0] * r0[1] + y0[1] * r0[0];
;                             z0[2] = y0[2] * r0[2] - y0[3] * r0[3]; z0[3] = y0[2] * r0[3] + y0[3] * r0[2];
;                             z1[0] = y1[0] * r1[0] - y1[1] * r1[1]; z1[1] = y1[0] * r1[1] + y1[1] * r1[0];
;                             z1[2] = y1[2] * r1[2] - y1[3] * r1[3]; z1[3] = y1[2] * r1[3] + y1[3] * r1[2];
;                             y0 = z0; y1 = z1;
;                         }
.LBB0_227:
	s_cmp_lt_i32 s36, 2
	s_cselect_b64 s[0:1], -1, 0
	v_readlane_b32 s56, v248, 18
	s_and_b64 s[14:15], s[0:1], exec
	v_readlane_b32 s57, v248, 19
	v_readlane_b32 s58, v248, 20
	v_readlane_b32 s59, v248, 21
	v_and_b32_e32 v186, 64, v229
	s_cselect_b32 s7, s57, s59
	s_cselect_b32 s25, s56, s58
	s_lshl_b64 s[14:15], s[76:77], 2
	v_xor_b32_e32 v176, 16, v229
	v_add_u32_e32 v186, 64, v186
	s_add_u32 s14, s25, s14
	v_cmp_lt_i32_e32 vcc, v176, v186
	s_addc_u32 s15, s7, s15
	s_lshl_b32 s25, s6, 8
	v_cndmask_b32_e32 v176, v229, v176, vcc
	s_add_i32 s25, s25, s75
	v_lshlrev_b32_e32 v201, 2, v176
	v_xor_b32_e32 v176, 32, v229
	v_cmp_lt_i32_e32 vcc, v176, v186
	v_or_b32_e32 v186, s25, v171
	v_ashrrev_i32_e32 v187, 31, v186
	v_cndmask_b32_e32 v176, v229, v176, vcc
	v_lshl_add_u64 v[188:189], v[186:187], 2, s[16:17]
	global_load_dwordx4 v[152:155], v200, s[14:15] offset:16
	global_load_dwordx4 v[156:159], v200, s[14:15]
	global_load_dwordx4 v[144:147], v200, s[14:15] offset:144
	global_load_dwordx4 v[148:151], v200, s[14:15] offset:128
	v_lshlrev_b32_e32 v202, 2, v176
	flat_load_dword v176, v[188:189]
	flat_load_dword v214, v[188:189] offset:64
	flat_load_dword v215, v[188:189] offset:128
	flat_load_dword v216, v[188:189] offset:192
	flat_load_dword v217, v[188:189] offset:512
	flat_load_dword v218, v[188:189] offset:576
	flat_load_dword v219, v[188:189] offset:640
	flat_load_dword v220, v[188:189] offset:704
	v_readlane_b32 s60, v248, 22
	v_readlane_b32 s61, v248, 23
	v_readlane_b32 s62, v248, 24
	v_readlane_b32 s63, v248, 25
	v_readlane_b32 s64, v248, 26
	v_readlane_b32 s65, v248, 27
	v_readlane_b32 s66, v248, 28
	v_readlane_b32 s67, v248, 29
	v_readlane_b32 s68, v248, 30
	v_readlane_b32 s69, v248, 31
	v_readlane_b32 s70, v248, 32
	v_readlane_b32 s71, v248, 33
	s_waitcnt vmcnt(0) lgkmcnt(0)
	v_fmamk_f32 v176, v176, 0x3a800000, v224
	v_cmp_gt_f32_e32 vcc, s33, v176
	v_mul_f32_e32 v187, 0x4b800000, v176
	s_nop 0
	v_cndmask_b32_e32 v176, v176, v187, vcc
	v_rsq_f32_e32 v176, v176
	s_nop 0
	v_mul_f32_e32 v187, 0x45800000, v176
	v_cndmask_b32_e32 v176, v176, v187, vcc
	v_pk_fma_f32 v[140:141], v[140:141], v[176:177], v[44:45] op_sel_hi:[1,0,1]
	v_pk_fma_f32 v[142:143], v[142:143], v[176:177], v[46:47] op_sel_hi:[1,0,1]
	v_pk_mul_f32 v[192:193], v[140:141], v[140:141]
	v_pk_mul_f32 v[190:191], v[142:143], v[142:143]
	v_pk_fma_f32 v[204:205], v[138:139], v[176:177], v[42:43] op_sel_hi:[1,0,1]
	v_pk_mov_b32 v[194:195], v[192:193], v[190:191] op_sel:[1,0]
	v_mov_b32_e32 v193, v191
	v_pk_add_f32 v[190:191], v[194:195], v[192:193]
	v_pk_fma_f32 v[192:193], v[136:137], v[176:177], v[40:41] op_sel_hi:[1,0,1]
	v_pk_mul_f32 v[136:137], v[204:205], v[204:205]
	v_pk_mul_f32 v[138:139], v[192:193], v[192:193]
	v_pk_fma_f32 v[132:133], v[132:133], v[176:177], v[36:37] op_sel_hi:[1,0,1]
	v_pk_mov_b32 v[194:195], v[138:139], v[136:137] op_sel:[1,0]
	v_mov_b32_e32 v139, v137
	v_pk_add_f32 v[136:137], v[194:195], v[138:139]
	v_pk_fma_f32 v[134:135], v[134:135], v[176:177], v[38:39] op_sel_hi:[1,0,1]
	v_pk_add_f32 v[138:139], v[136:137], v[136:137] op_sel_hi:[0,1]
	v_mul_f32_e32 v136, v132, v132
	v_pk_fma_f32 v[194:195], v[132:133], v[132:133], v[136:137] op_sel_hi:[1,1,0]
	v_mul_f32_e32 v136, v134, v134
	v_pk_add_f32 v[190:191], v[190:191], v[190:191] op_sel_hi:[0,1]
	v_pk_fma_f32 v[206:207], v[134:135], v[134:135], v[136:137] op_sel_hi:[1,1,0]
	v_pk_fma_f32 v[130:131], v[130:131], v[176:177], v[34:35] op_sel_hi:[1,0,1]
	v_pk_fma_f32 v[136:137], v[128:129], v[176:177], v[32:33] op_sel_hi:[1,0,1]
	v_mul_f32_e32 v190, v130, v130
	v_mul_f32_e32 v194, v136, v136
	v_mul_f32_e32 v206, v137, v137
	v_mul_f32_e32 v138, v131, v131
	v_pk_add_f32 v[128:129], v[194:195], v[206:207]
	v_pk_add_f32 v[138:139], v[190:191], v[138:139]
	s_nop 0
	v_pk_add_f32 v[128:129], v[128:129], v[138:139]
	s_nop 0
	v_add_f32_e32 v128, v128, v129
	ds_bpermute_b32 v129, v201, v128
	s_waitcnt lgkmcnt(0)
	v_add_f32_e32 v128, v128, v129
	ds_bpermute_b32 v129, v202, v128
	s_waitcnt lgkmcnt(0)
	v_add_f32_e32 v128, v128, v129
	v_fmamk_f32 v128, v128, 0x3c800000, v224
	v_cmp_gt_f32_e32 vcc, s33, v128
	v_mul_f32_e32 v129, 0x4b800000, v128
	s_nop 0
	v_cndmask_b32_e32 v128, v128, v129, vcc
	v_rsq_f32_e32 v128, v128
	s_nop 0
	v_mul_f32_e32 v129, 0x45800000, v128
	v_cndmask_b32_e32 v138, v128, v129, vcc
	v_pk_mul_f32 v[128:129], v[140:141], v[138:139] op_sel_hi:[1,0]
	v_pk_mul_f32 v[140:141], v[142:143], v[138:139] op_sel_hi:[1,0]
	v_pk_mul_f32 v[142:143], v[156:157], v[128:129]
	v_pk_mul_f32 v[194:195], v[158:159], v[140:141]
	v_pk_mul_f32 v[128:129], v[192:193], v[138:139] op_sel_hi:[1,0]
	v_pk_mul_f32 v[140:141], v[204:205], v[138:139] op_sel_hi:[1,0]
	s_andn2_b64 vcc, exec, s[54:55]
	v_pk_mul_f32 v[190:191], v[154:155], v[140:141]
	v_pk_mul_f32 v[140:141], v[152:153], v[128:129]
	v_cndmask_b32_e64 v128, 0, 1, s[54:55]
	v_cmp_ne_u32_e64 s[6:7], 1, v128
	s_cbranch_vccnz .LBB0_229
	s_lshr_b32 s14, s25, 1
	s_and_b32 s14, s14, 0xfe0
	v_or_b32_e32 v128, s14, v168
	v_lshlrev_b32_e32 v176, 2, v128
	v_lshl_add_u64 v[128:129], s[18:19], 0, v[176:177]
	flat_load_dwordx4 v[204:207], v[128:129]
	flat_load_dwordx4 v[208:211], v[128:129] offset:16
	s_waitcnt vmcnt(0) lgkmcnt(0)
	v_pk_mul_f32 v[192:193], v[142:143], v[204:205] op_sel:[1,1] op_sel_hi:[1,0]
	v_pk_mul_f32 v[128:129], v[142:143], v[204:205]
	v_pk_fma_f32 v[142:143], v[142:143], v[204:205], v[192:193] op_sel_hi:[0,1,1]
	v_mul_f32_e32 v142, v195, v207
	v_pk_fma_f32 v[204:205], v[194:195], v[206:207], v[142:143] op_sel_hi:[1,1,0] neg_lo:[0,0,1] neg_hi:[0,0,1]
	v_mul_f32_e32 v142, v195, v206
	v_pk_mul_f32 v[212:213], v[140:141], v[208:209] op_sel:[1,1] op_sel_hi:[1,0]
	v_pk_fma_f32 v[206:207], v[194:195], v[206:207], v[142:143] op_sel:[0,1,0] op_sel_hi:[1,0,0]
	v_pk_mul_f32 v[194:195], v[140:141], v[208:209]
	v_pk_fma_f32 v[140:141], v[140:141], v[208:209], v[212:213] op_sel_hi:[0,1,1]
	v_mul_f32_e32 v140, v191, v211
	v_pk_fma_f32 v[208:209], v[190:191], v[210:211], v[140:141] op_sel_hi:[1,1,0] neg_lo:[0,0,1] neg_hi:[0,0,1]
	v_mul_f32_e32 v140, v191, v210
	v_pk_fma_f32 v[210:211], v[190:191], v[210:211], v[140:141] op_sel:[0,1,0] op_sel_hi:[1,0,0]
	v_sub_f32_e32 v140, v194, v212
	v_sub_f32_e32 v142, v128, v192
	v_mov_b32_e32 v190, v208
	v_mov_b32_e32 v191, v210
	v_mov_b32_e32 v194, v204
	v_mov_b32_e32 v195, v206

;     __device__ __forceinline__ void operator()(const f32x4 (&acc)[2][2][4][2], const Unit& u, int wr, int wc, int fr, int fq) const {
;     ...
;                     const float rinv = rsqrtf(rowsq[row] * (1.f / DM) + EPSN);
;                     int b, kidx, t = 0;
;                     if (isctx) { const int rc = row - MLAT; b = rc >> 8; kidx = rc & 255; } else { b = row >> 13; t = row & (SEQ - 1); kidx = CTXL + t; }
;                     f32x4 val[2][2]; float ss = 0.f;
; #pragma unroll
;                     for (int bj = 0; bj < 2; ++bj)
; #pragma unroll
;                         for (int n = 0; n < 2; ++n) { val[bj][n] = acc[ai][bj][m][n] * rinv + bv[bj][n]; const f32x4 q = val[bj][n]; ss += (q[0] * q[0] + q[1] * q[1]) + (q[2] * q[2] + q[3] * q[3]); }
;                     ss += __shfl_xor(ss, 16); ss += __shfl_xor(ss, 32);
;                     const float rn = rsqrtf(ss * (1.f / 64.f) + EPSN);
; #pragma unroll
;                     for (int bj = 0; bj < 2; ++bj) {
;                         f32x4 y0 = val[bj][0] * rn * gv[bj][0], y1 = val[bj][1] * rn * gv[bj][1];
;                         if (!isctx) {
;                             const int pos = bj == 0 ? (t >> 6) : (t & 63);
;                             const f32x4 r0 = *(const f32x4*)(rope + (size_t)(pos * 16 + 4 * fq) * 2);
;                             const f32x4 r1 = *(const f32x4*)(rope + (size_t)(pos * 16 + 4 * fq + 2) * 2);
;                             f32x4 z0, z1;
;                             z0[0] = y0[0] * r0[0] - y0[1] * r0[1]; z0[1] = y0[0] * r0[1] + y0[1] * r0[0];
;                             z0[2] = y0[2] * r0[2] - y0[3] * r0[3]; z0[3] = y0[2] * r0[3] + y0[3] * r0[2];
;                             z1[0] = y1[0] * r1[0] - y1[1] * r1[1]; z1[1] = y1[0] * r1[1] + y1[1] * r1[0];
;                             z1[2] = y1[2] * r1[2] - y1[3] * r1[3]; z1[3] = y1[2] * r1[3] + y1[3] * r1[2];
;                             y0 = z0; y1 = z1;
;                         }
;                         y0 = y0 * osc; y1 = y1 * osc;
;                         u32x4 w; w.x = pkbf(y0[0], y0[1]); w.y = pkbf(y0[2], y0[3]); w.z = pkbf(y1[0], y1[1]); w.w = pkbf(y1[2], y1[3]);
;                         const size_t off = (size_t)(b * 8 + hc) * (LK * 64) + (size_t)(kidx >> 6) * 4096 + (size_t)(4 * bj + fq) * 512 + (size_t)(kidx & 63) * 8;
;                         *(u32x4*)(dst + off) = w;
.LBB0_231:
	v_mov_b32_e32 v129, v128
	v_mov_b32_e32 v132, v128
	v_mov_b32_e32 v133, v128
	v_pk_mul_f32 v[134:135], v[128:129], v[134:135]
	v_pk_mul_f32 v[130:131], v[128:129], v[130:131]
	v_pk_mul_f32 v[138:139], v[132:133], v[140:141]
	v_pk_mul_f32 v[140:141], v[132:133], v[136:137]
	v_cvt_pk_bf16_f32 v134, v134, v135
	v_cvt_pk_bf16_f32 v135, v138, v139
	v_cvt_pk_bf16_f32 v136, v130, v131
	v_lshlrev_b32_e32 v130, 1, v172
	v_mov_b32_e32 v131, v177
	v_lshl_add_u64 v[138:139], v[192:193], 0, v[130:131]
	v_cvt_pk_bf16_f32 v137, v140, v141
	flat_store_dwordx4 v[138:139], v[134:137]
	s_nop 1
	s_movk_i32 s68, 0x1fff
	v_fmamk_f32 v131, v214, 0x3a800000, v224
	v_cmp_gt_f32_e32 vcc, s33, v131
	v_mul_f32_e32 v134, 0x4b800000, v131
	s_nop 0
	v_cndmask_b32_e32 v131, v131, v134, vcc
	v_rsq_f32_e32 v131, v131
	s_nop 0
	v_mul_f32_e32 v134, 0x45800000, v131
	v_cndmask_b32_e32 v134, v131, v134, vcc
	v_pk_fma_f32 v[124:125], v[124:125], v[134:135], v[44:45] op_sel_hi:[1,0,1]
	v_pk_fma_f32 v[126:127], v[126:127], v[134:135], v[46:47] op_sel_hi:[1,0,1]
	v_pk_mul_f32 v[138:139], v[124:125], v[124:125]
	v_pk_mul_f32 v[136:137], v[126:127], v[126:127]
	v_pk_fma_f32 v[122:123], v[122:123], v[134:135], v[42:43] op_sel_hi:[1,0,1]
	v_pk_mov_b32 v[140:141], v[138:139], v[136:137] op_sel:[1,0]
	v_mov_b32_e32 v139, v137
	v_pk_add_f32 v[136:137], v[140:141], v[138:139]
	v_pk_fma_f32 v[138:139], v[120:121], v[134:135], v[40:41] op_sel_hi:[1,0,1]
	v_pk_mul_f32 v[120:121], v[122:123], v[122:123]
	v_pk_mul_f32 v[140:141], v[138:139], v[138:139]
	v_pk_fma_f32 v[116:117], v[116:117], v[134:135], v[36:37] op_sel_hi:[1,0,1]
	v_pk_mov_b32 v[142:143], v[140:141], v[120:121] op_sel:[1,0]
	v_mov_b32_e32 v141, v121
	v_pk_add_f32 v[120:121], v[142:143], v[140:141]
	v_pk_fma_f32 v[118:119], v[118:119], v[134:135], v[38:39] op_sel_hi:[1,0,1]
	v_pk_add_f32 v[120:121], v[120:121], v[120:121] op_sel_hi:[0,1]
	v_mul_f32_e32 v120, v116, v116
	v_pk_fma_f32 v[140:141], v[116:117], v[116:117], v[120:121] op_sel_hi:[1,1,0]
	v_mul_f32_e32 v120, v118, v118
	v_pk_add_f32 v[136:137], v[136:137], v[136:137] op_sel_hi:[0,1]
	v_pk_fma_f32 v[142:143], v[118:119], v[118:119], v[120:121] op_sel_hi:[1,1,0]
	v_pk_fma_f32 v[114:115], v[114:115], v[134:135], v[34:35] op_sel_hi:[1,0,1]
	v_pk_fma_f32 v[112:113], v[112:113], v[134:135], v[32:33] op_sel_hi:[1,0,1]
	v_mul_f32_e32 v136, v114, v114
	v_mul_f32_e32 v140, v112, v112
	v_mul_f32_e32 v142, v113, v113
	v_mul_f32_e32 v120, v115, v115
	v_pk_add_f32 v[134:135], v[140:141], v[142:143]
	v_pk_add_f32 v[120:121], v[136:137], v[120:121]
	s_nop 0
	v_pk_add_f32 v[120:121], v[134:135], v[120:121]
	s_nop 0
	v_add_f32_e32 v120, v120, v121
	ds_bpermute_b32 v121, v201, v120
	s_waitcnt lgkmcnt(0)
	v_add_f32_e32 v120, v120, v121
	ds_bpermute_b32 v121, v202, v120
	s_waitcnt lgkmcnt(0)
	v_add_f32_e32 v120, v120, v121
	v_fmamk_f32 v120, v120, 0x3c800000, v224
	v_cmp_gt_f32_e32 vcc, s33, v120
	v_mul_f32_e32 v121, 0x4b800000, v120
	s_nop 0
	v_cndmask_b32_e32 v120, v120, v121, vcc
	v_rsq_f32_e32 v120, v120
	s_nop 0
	v_mul_f32_e32 v121, 0x45800000, v120
	v_cndmask_b32_e32 v120, v120, v121, vcc
	v_pk_mul_f32 v[124:125], v[124:125], v[120:121] op_sel_hi:[1,0]
	v_pk_mul_f32 v[126:127], v[126:127], v[120:121] op_sel_hi:[1,0]
	v_pk_mul_f32 v[134:135], v[138:139], v[120:121] op_sel_hi:[1,0]
	v_pk_mul_f32 v[122:123], v[122:123], v[120:121] op_sel_hi:[1,0]
	v_pk_mul_f32 v[136:137], v[158:159], v[126:127]
	v_pk_mul_f32 v[124:125], v[156:157], v[124:125]
	v_pk_mul_f32 v[126:127], v[154:155], v[122:123]
	v_pk_mul_f32 v[122:123], v[152:153], v[134:135]
	s_and_b64 vcc, exec, s[6:7]
	s_cbranch_vccnz .LBB0_233
	s_lshr_b32 s0, s25, 1
	s_and_b32 s0, s0, 0xfe0
	v_or_b32_e32 v121, s0, v168
	v_lshlrev_b32_e32 v134, 2, v121
	v_mov_b32_e32 v135, v177
	v_lshl_add_u64 v[134:135], s[18:19], 0, v[134:135]
	flat_load_dwordx4 v[138:141], v[134:135]
	flat_load_dwordx4 v[190:193], v[134:135] offset:16
	s_waitcnt vmcnt(0) lgkmcnt(0)
	v_pk_mul_f32 v[142:143], v[124:125], v[138:139] op_sel:[1,1] op_sel_hi:[1,0]
	v_pk_mul_f32 v[134:135], v[124:125], v[138:139]
	v_pk_fma_f32 v[124:125], v[124:125], v[138:139], v[142:143] op_sel_hi:[0,1,1]
	v_mul_f32_e32 v124, v137, v141
	v_pk_fma_f32 v[138:139], v[136:137], v[140:141], v[124:125] op_sel_hi:[1,1,0] neg_lo:[0,0,1] neg_hi:[0,0,1]
	v_mul_f32_e32 v124, v137, v140
	v_pk_mul_f32 v[194:195], v[122:123], v[190:191] op_sel:[1,1] op_sel_hi:[1,0]
	v_pk_fma_f32 v[140:141], v[136:137], v[140:141], v[124:125] op_sel:[0,1,0] op_sel_hi:[1,0,0]
	v_pk_mul_f32 v[136:137], v[122:123], v[190:191]
	v_pk_fma_f32 v[122:123], v[122:123], v[190:191], v[194:195] op_sel_hi:[0,1,1]
	v_mul_f32_e32 v122, v127, v193
	v_pk_fma_f32 v[190:191], v[126:127], v[192:193], v[122:123] op_sel_hi:[1,1,0] neg_lo:[0,0,1] neg_hi:[0,0,1]
	v_mul_f32_e32 v122, v127, v192
	v_pk_fma_f32 v[192:193], v[126:127], v[192:193], v[122:123] op_sel:[0,1,0] op_sel_hi:[1,0,0]
	v_sub_f32_e32 v122, v136, v194
	v_sub_f32_e32 v124, v134, v142
	v_mov_b32_e32 v126, v190
	v_mov_b32_e32 v127, v192
	v_mov_b32_e32 v136, v138
	v_mov_b32_e32 v137, v140

;     __device__ __forceinline__ void operator()(const f32x4 (&acc)[2][2][4][2], const Unit& u, int wr, int wc, int fr, int fq) const {
;     ...
;                     const float rinv = rsqrtf(rowsq[row] * (1.f / DM) + EPSN);
;                     int b, kidx, t = 0;
;                     if (isctx) { const int rc = row - MLAT; b = rc >> 8; kidx = rc & 255; } else { b = row >> 13; t = row & (SEQ - 1); kidx = CTXL + t; }
;                     f32x4 val[2][2]; float ss = 0.f;
; #pragma unroll
;                     for (int bj = 0; bj < 2; ++bj)
; #pragma unroll
;                         for (int n = 0; n < 2; ++n) { val[bj][n] = acc[ai][bj][m][n] * rinv + bv[bj][n]; const f32x4 q = val[bj][n]; ss += (q[0] * q[0] + q[1] * q[1]) + (q[2] * q[2] + q[3] * q[3]); }
;                     ss += __shfl_xor(ss, 16); ss += __shfl_xor(ss, 32);
;                     const float rn = rsqrtf(ss * (1.f / 64.f) + EPSN);
; #pragma unroll
;                     for (int bj = 0; bj < 2; ++bj) {
;                         f32x4 y0 = val[bj][0] * rn * gv[bj][0], y1 = val[bj][1] * rn * gv[bj][1];
;                         if (!isctx) {
;                             const int pos = bj == 0 ? (t >> 6) : (t & 63);
;                             const f32x4 r0 = *(const f32x4*)(rope + (size_t)(pos * 16 + 4 * fq) * 2);
;                             const f32x4 r1 = *(const f32x4*)(rope + (size_t)(pos * 16 + 4 * fq + 2) * 2);
;                             f32x4 z0, z1;
;                             z0[0] = y0[0] * r0[0] - y0[1] * r0[1]; z0[1] = y0[0] * r0[1] + y0[1] * r0[0];
;                             z0[2] = y0[2] * r0[2] - y0[3] * r0[3]; z0[3] = y0[2] * r0[3] + y0[3] * r0[2];
;                             z1[0] = y1[0] * r1[0] - y1[1] * r1[1]; z1[1] = y1[0] * r1[1] + y1[1] * r1[0];
;                             z1[2] = y1[2] * r1[2] - y1[3] * r1[3]; z1[3] = y1[2] * r1[3] + y1[3] * r1[2];
;                             y0 = z0; y1 = z1;
;                         }
;                         y0 = y0 * osc; y1 = y1 * osc;
;                         u32x4 w; w.x = pkbf(y0[0], y0[1]); w.y = pkbf(y0[2], y0[3]); w.z = pkbf(y1[0], y1[1]); w.w = pkbf(y1[2], y1[3]);
;                         const size_t off = (size_t)(b * 8 + hc) * (LK * 64) + (size_t)(kidx >> 6) * 4096 + (size_t)(4 * bj + fq) * 512 + (size_t)(kidx & 63) * 8;
;                         *(u32x4*)(dst + off) = w;
.LBB0_235:
	v_mov_b32_e32 v112, v128
	v_mov_b32_e32 v113, v128
	v_pk_mul_f32 v[116:117], v[128:129], v[116:117]
	v_pk_mul_f32 v[118:119], v[112:113], v[118:119]
	v_mov_b32_e32 v131, v177
	v_pk_mul_f32 v[120:121], v[112:113], v[122:123]
	v_pk_mul_f32 v[122:123], v[128:129], v[114:115]
	v_cvt_pk_bf16_f32 v114, v116, v117
	v_cvt_pk_bf16_f32 v115, v120, v121
	s_nop 0
	v_cvt_pk_bf16_f32 v116, v122, v123
	v_cvt_pk_bf16_f32 v117, v118, v119
	v_lshl_add_u64 v[118:119], v[134:135], 0, v[130:131]
	flat_store_dwordx4 v[118:119], v[114:117]
	s_nop 1
	v_fmamk_f32 v114, v215, 0x3a800000, v224
	v_mul_f32_e32 v115, 0x4b800000, v114
	v_cmp_gt_f32_e32 vcc, s33, v114
	s_nop 1
	v_cndmask_b32_e32 v114, v114, v115, vcc
	v_rsq_f32_e32 v114, v114
	s_nop 0
	v_mul_f32_e32 v115, 0x45800000, v114
	v_cndmask_b32_e32 v114, v114, v115, vcc
	v_pk_fma_f32 v[108:109], v[108:109], v[114:115], v[44:45] op_sel_hi:[1,0,1]
	v_pk_fma_f32 v[110:111], v[110:111], v[114:115], v[46:47] op_sel_hi:[1,0,1]
	v_pk_fma_f32 v[104:105], v[104:105], v[114:115], v[40:41] op_sel_hi:[1,0,1]
	v_pk_fma_f32 v[116:117], v[106:107], v[114:115], v[42:43] op_sel_hi:[1,0,1]
	v_pk_fma_f32 v[102:103], v[102:103], v[114:115], v[38:39] op_sel_hi:[1,0,1]
	v_pk_fma_f32 v[100:101], v[100:101], v[114:115], v[36:37] op_sel_hi:[1,0,1]
	v_pk_fma_f32 v[98:99], v[98:99], v[114:115], v[34:35] op_sel_hi:[1,0,1]
	v_pk_fma_f32 v[96:97], v[96:97], v[114:115], v[32:33] op_sel_hi:[1,0,1]
	v_pk_mul_f32 v[106:107], v[110:111], v[110:111]
	v_pk_mul_f32 v[114:115], v[108:109], v[108:109]
	v_pk_mul_f32 v[118:119], v[116:117], v[116:117]
	v_pk_mul_f32 v[120:121], v[104:105], v[104:105]
	v_pk_mov_b32 v[126:127], v[114:115], v[106:107] op_sel:[1,0]
	v_mov_b32_e32 v115, v107
	v_pk_mov_b32 v[106:107], v[120:121], v[118:119] op_sel:[1,0]
	v_mov_b32_e32 v121, v119
	v_mul_f32_e32 v122, v100, v100
	v_mul_f32_e32 v124, v102, v102
	v_pk_add_f32 v[114:115], v[126:127], v[114:115]
	v_pk_add_f32 v[106:107], v[106:107], v[120:121]
	v_pk_fma_f32 v[118:119], v[100:101], v[100:101], v[122:123] op_sel_hi:[1,1,0]
	v_pk_fma_f32 v[122:123], v[102:103], v[102:103], v[124:125] op_sel_hi:[1,1,0]
	v_pk_add_f32 v[114:115], v[114:115], v[114:115] op_sel_hi:[0,1]
	v_pk_add_f32 v[106:107], v[106:107], v[106:107] op_sel_hi:[0,1]
	v_mul_f32_e32 v118, v96, v96
	v_mul_f32_e32 v122, v97, v97
	v_mul_f32_e32 v114, v98, v98
	v_mul_f32_e32 v106, v99, v99
	v_pk_add_f32 v[118:119], v[118:119], v[122:123]
	v_pk_add_f32 v[106:107], v[114:115], v[106:107]
	s_and_b64 vcc, exec, s[6:7]
	v_pk_add_f32 v[106:107], v[118:119], v[106:107]
	s_nop 0
	v_add_f32_e32 v106, v106, v107
	ds_bpermute_b32 v107, v201, v106
	s_waitcnt lgkmcnt(0)
	v_add_f32_e32 v106, v106, v107
	ds_bpermute_b32 v107, v202, v106
	s_waitcnt lgkmcnt(0)
	v_add_f32_e32 v106, v106, v107
	v_fmamk_f32 v106, v106, 0x3c800000, v224
	v_mul_f32_e32 v107, 0x4b800000, v106
	v_cmp_gt_f32_e64 s[0:1], s33, v106
	s_nop 1
	v_cndmask_b32_e64 v106, v106, v107, s[0:1]
	v_rsq_f32_e32 v106, v106
	s_nop 0
	v_mul_f32_e32 v107, 0x45800000, v106
	v_cndmask_b32_e64 v106, v106, v107, s[0:1]
	v_pk_mul_f32 v[108:109], v[108:109], v[106:107] op_sel_hi:[1,0]
	v_pk_mul_f32 v[110:111], v[110:111], v[106:107] op_sel_hi:[1,0]
	v_pk_mul_f32 v[104:105], v[104:105], v[106:107] op_sel_hi:[1,0]
	v_pk_mul_f32 v[114:115], v[116:117], v[106:107] op_sel_hi:[1,0]
	v_pk_mul_f32 v[116:117], v[158:159], v[110:111]
	v_pk_mul_f32 v[110:111], v[156:157], v[108:109]
	v_pk_mul_f32 v[114:115], v[154:155], v[114:115]
	v_pk_mul_f32 v[108:109], v[152:153], v[104:105]
	s_cbranch_vccnz .LBB0_237
	s_lshr_b32 s0, s25, 1
	s_and_b32 s0, s0, 0xfe0
	v_or_b32_e32 v104, s0, v168
	v_lshlrev_b32_e32 v104, 2, v104
	v_mov_b32_e32 v105, v177
	v_lshl_add_u64 v[104:105], s[18:19], 0, v[104:105]
	flat_load_dwordx4 v[118:121], v[104:105]
	flat_load_dwordx4 v[122:125], v[104:105] offset:16
	s_waitcnt vmcnt(0) lgkmcnt(0)
	v_pk_mul_f32 v[126:127], v[110:111], v[118:119] op_sel:[1,1] op_sel_hi:[1,0]
	v_pk_mul_f32 v[104:105], v[110:111], v[118:119]
	v_pk_fma_f32 v[110:111], v[110:111], v[118:119], v[126:127] op_sel_hi:[0,1,1]
	v_mul_f32_e32 v110, v117, v121
	v_pk_fma_f32 v[118:119], v[116:117], v[120:121], v[110:111] op_sel_hi:[1,1,0] neg_lo:[0,0,1] neg_hi:[0,0,1]
	v_mul_f32_e32 v110, v117, v120
	v_pk_mul_f32 v[132:133], v[108:109], v[122:123] op_sel:[1,1] op_sel_hi:[1,0]
	v_pk_fma_f32 v[120:121], v[116:117], v[120:121], v[110:111] op_sel:[0,1,0] op_sel_hi:[1,0,0]
	v_pk_mul_f32 v[116:117], v[108:109], v[122:123]
	v_pk_fma_f32 v[108:109], v[108:109], v[122:123], v[132:133] op_sel_hi:[0,1,1]
	v_mul_f32_e32 v108, v115, v125
	v_pk_fma_f32 v[122:123], v[114:115], v[124:125], v[108:109] op_sel_hi:[1,1,0] neg_lo:[0,0,1] neg_hi:[0,0,1]
	v_mul_f32_e32 v108, v115, v124
	v_pk_fma_f32 v[124:125], v[114:115], v[124:125], v[108:109] op_sel:[0,1,0] op_sel_hi:[1,0,0]
	v_sub_f32_e32 v108, v116, v132
	v_sub_f32_e32 v110, v104, v126
	v_mov_b32_e32 v114, v122
	v_mov_b32_e32 v115, v124
	v_mov_b32_e32 v116, v118
	v_mov_b32_e32 v117, v120

;     __device__ __forceinline__ void operator()(const f32x4 (&acc)[2][2][4][2], const Unit& u, int wr, int wc, int fr, int fq) const {
;     ...
;                     const float rinv = rsqrtf(rowsq[row] * (1.f / DM) + EPSN);
;                     int b, kidx, t = 0;
;                     if (isctx) { const int rc = row - MLAT; b = rc >> 8; kidx = rc & 255; } else { b = row >> 13; t = row & (SEQ - 1); kidx = CTXL + t; }
;                     f32x4 val[2][2]; float ss = 0.f;
; #pragma unroll
;                     for (int bj = 0; bj < 2; ++bj)
; #pragma unroll
;                         for (int n = 0; n < 2; ++n) { val[bj][n] = acc[ai][bj][m][n] * rinv + bv[bj][n]; const f32x4 q = val[bj][n]; ss += (q[0] * q[0] + q[1] * q[1]) + (q[2] * q[2] + q[3] * q[3]); }
;                     ss += __shfl_xor(ss, 16); ss += __shfl_xor(ss, 32);
;                     const float rn = rsqrtf(ss * (1.f / 64.f) + EPSN);
; #pragma unroll
;                     for (int bj = 0; bj < 2; ++bj) {
;                         f32x4 y0 = val[bj][0] * rn * gv[bj][0], y1 = val[bj][1] * rn * gv[bj][1];
;                         if (!isctx) {
;                             const int pos = bj == 0 ? (t >> 6) : (t & 63);
;                             const f32x4 r0 = *(const f32x4*)(rope + (size_t)(pos * 16 + 4 * fq) * 2);
;                             const f32x4 r1 = *(const f32x4*)(rope + (size_t)(pos * 16 + 4 * fq + 2) * 2);
;                             f32x4 z0, z1;
;                             z0[0] = y0[0] * r0[0] - y0[1] * r0[1]; z0[1] = y0[0] * r0[1] + y0[1] * r0[0];
;                             z0[2] = y0[2] * r0[2] - y0[3] * r0[3]; z0[3] = y0[2] * r0[3] + y0[3] * r0[2];
;                             z1[0] = y1[0] * r1[0] - y1[1] * r1[1]; z1[1] = y1[0] * r1[1] + y1[1] * r1[0];
;                             z1[2] = y1[2] * r1[2] - y1[3] * r1[3]; z1[3] = y1[2] * r1[3] + y1[3] * r1[2];
;                             y0 = z0; y1 = z1;
;                         }
;                         y0 = y0 * osc; y1 = y1 * osc;
;                         u32x4 w; w.x = pkbf(y0[0], y0[1]); w.y = pkbf(y0[2], y0[3]); w.z = pkbf(y1[0], y1[1]); w.w = pkbf(y1[2], y1[3]);
;                         const size_t off = (size_t)(b * 8 + hc) * (LK * 64) + (size_t)(kidx >> 6) * 4096 + (size_t)(4 * bj + fq) * 512 + (size_t)(kidx & 63) * 8;
;                         *(u32x4*)(dst + off) = w;
.LBB0_239:
	v_mov_b32_e32 v96, v128
	v_mov_b32_e32 v97, v128
	v_pk_mul_f32 v[100:101], v[128:129], v[100:101]
	v_pk_mul_f32 v[102:103], v[96:97], v[102:103]
	v_mov_b32_e32 v131, v177
	v_pk_mul_f32 v[106:107], v[96:97], v[108:109]
	v_pk_mul_f32 v[108:109], v[128:129], v[98:99]
	v_cvt_pk_bf16_f32 v98, v100, v101
	v_cvt_pk_bf16_f32 v99, v106, v107
	s_nop 0
	v_cvt_pk_bf16_f32 v100, v108, v109
	v_cvt_pk_bf16_f32 v101, v102, v103
	v_lshl_add_u64 v[102:103], v[104:105], 0, v[130:131]
	flat_store_dwordx4 v[102:103], v[98:101]
	s_nop 1
	v_fmamk_f32 v98, v216, 0x3a800000, v224
	v_mul_f32_e32 v99, 0x4b800000, v98
	v_cmp_gt_f32_e32 vcc, s33, v98
	s_nop 1
	v_cndmask_b32_e32 v98, v98, v99, vcc
	v_rsq_f32_e32 v98, v98
	s_nop 0
	v_mul_f32_e32 v99, 0x45800000, v98
	v_cndmask_b32_e32 v98, v98, v99, vcc
	v_pk_fma_f32 v[92:93], v[92:93], v[98:99], v[44:45] op_sel_hi:[1,0,1]
	v_pk_fma_f32 v[94:95], v[94:95], v[98:99], v[46:47] op_sel_hi:[1,0,1]
	v_pk_fma_f32 v[88:89], v[88:89], v[98:99], v[40:41] op_sel_hi:[1,0,1]
	v_pk_fma_f32 v[100:101], v[90:91], v[98:99], v[42:43] op_sel_hi:[1,0,1]
	v_pk_fma_f32 v[86:87], v[86:87], v[98:99], v[38:39] op_sel_hi:[1,0,1]
	v_pk_fma_f32 v[84:85], v[84:85], v[98:99], v[36:37] op_sel_hi:[1,0,1]
	v_pk_fma_f32 v[82:83], v[82:83], v[98:99], v[34:35] op_sel_hi:[1,0,1]
	v_pk_fma_f32 v[80:81], v[80:81], v[98:99], v[32:33] op_sel_hi:[1,0,1]
	v_pk_mul_f32 v[90:91], v[94:95], v[94:95]
	v_pk_mul_f32 v[98:99], v[92:93], v[92:93]
	v_pk_mul_f32 v[102:103], v[100:101], v[100:101]
	v_pk_mul_f32 v[104:105], v[88:89], v[88:89]
	v_pk_mov_b32 v[110:111], v[98:99], v[90:91] op_sel:[1,0]
	v_mov_b32_e32 v99, v91
	v_pk_mov_b32 v[90:91], v[104:105], v[102:103] op_sel:[1,0]
	v_mov_b32_e32 v105, v103
	v_mul_f32_e32 v106, v84, v84
	v_mul_f32_e32 v108, v86, v86
	v_pk_add_f32 v[98:99], v[110:111], v[98:99]
	v_pk_add_f32 v[90:91], v[90:91], v[104:105]
	v_pk_fma_f32 v[102:103], v[84:85], v[84:85], v[106:107] op_sel_hi:[1,1,0]
	v_pk_fma_f32 v[106:107], v[86:87], v[86:87], v[108:109] op_sel_hi:[1,1,0]
	v_pk_add_f32 v[98:99], v[98:99], v[98:99] op_sel_hi:[0,1]
	v_pk_add_f32 v[90:91], v[90:91], v[90:91] op_sel_hi:[0,1]
	v_mul_f32_e32 v102, v80, v80
	v_mul_f32_e32 v106, v81, v81
	v_mul_f32_e32 v98, v82, v82
	v_mul_f32_e32 v90, v83, v83
	v_pk_add_f32 v[102:103], v[102:103], v[106:107]
	v_pk_add_f32 v[90:91], v[98:99], v[90:91]
	s_and_b64 vcc, exec, s[6:7]
	v_pk_add_f32 v[90:91], v[102:103], v[90:91]
	s_nop 0
	v_add_f32_e32 v90, v90, v91
	ds_bpermute_b32 v91, v201, v90
	s_waitcnt lgkmcnt(0)
	v_add_f32_e32 v90, v90, v91
	ds_bpermute_b32 v91, v202, v90
	s_waitcnt lgkmcnt(0)
	v_add_f32_e32 v90, v90, v91
	v_fmamk_f32 v90, v90, 0x3c800000, v224
	v_mul_f32_e32 v91, 0x4b800000, v90
	v_cmp_gt_f32_e64 s[0:1], s33, v90
	s_nop 1
	v_cndmask_b32_e64 v90, v90, v91, s[0:1]
	v_rsq_f32_e32 v90, v90
	s_nop 0
	v_mul_f32_e32 v91, 0x45800000, v90
	v_cndmask_b32_e64 v90, v90, v91, s[0:1]
	v_pk_mul_f32 v[92:93], v[92:93], v[90:91] op_sel_hi:[1,0]
	v_pk_mul_f32 v[94:95], v[94:95], v[90:91] op_sel_hi:[1,0]
	v_pk_mul_f32 v[88:89], v[88:89], v[90:91] op_sel_hi:[1,0]
	v_pk_mul_f32 v[98:99], v[100:101], v[90:91] op_sel_hi:[1,0]
	v_pk_mul_f32 v[100:101], v[158:159], v[94:95]
	v_pk_mul_f32 v[94:95], v[156:157], v[92:93]
	v_pk_mul_f32 v[98:99], v[154:155], v[98:99]
	v_pk_mul_f32 v[92:93], v[152:153], v[88:89]
	s_cbranch_vccnz .LBB0_241
	s_lshr_b32 s0, s25, 1
	s_and_b32 s0, s0, 0xfe0
	v_or_b32_e32 v88, s0, v168
	v_lshlrev_b32_e32 v88, 2, v88
	v_mov_b32_e32 v89, v177
	v_lshl_add_u64 v[88:89], s[18:19], 0, v[88:89]
	flat_load_dwordx4 v[102:105], v[88:89]
	flat_load_dwordx4 v[106:109], v[88:89] offset:16
	s_waitcnt vmcnt(0) lgkmcnt(0)
	v_pk_mul_f32 v[110:111], v[94:95], v[102:103] op_sel:[1,1] op_sel_hi:[1,0]
	v_pk_mul_f32 v[88:89], v[94:95], v[102:103]
	v_pk_fma_f32 v[94:95], v[94:95], v[102:103], v[110:111] op_sel_hi:[0,1,1]
	v_mul_f32_e32 v94, v101, v105
	v_pk_fma_f32 v[102:103], v[100:101], v[104:105], v[94:95] op_sel_hi:[1,1,0] neg_lo:[0,0,1] neg_hi:[0,0,1]
	v_mul_f32_e32 v94, v101, v104
	v_pk_mul_f32 v[112:113], v[92:93], v[106:107] op_sel:[1,1] op_sel_hi:[1,0]
	v_pk_fma_f32 v[104:105], v[100:101], v[104:105], v[94:95] op_sel:[0,1,0] op_sel_hi:[1,0,0]
	v_pk_mul_f32 v[100:101], v[92:93], v[106:107]
	v_pk_fma_f32 v[92:93], v[92:93], v[106:107], v[112:113] op_sel_hi:[0,1,1]
	v_mul_f32_e32 v92, v99, v109
	v_pk_fma_f32 v[106:107], v[98:99], v[108:109], v[92:93] op_sel_hi:[1,1,0] neg_lo:[0,0,1] neg_hi:[0,0,1]
	v_mul_f32_e32 v92, v99, v108
	v_pk_fma_f32 v[108:109], v[98:99], v[108:109], v[92:93] op_sel:[0,1,0] op_sel_hi:[1,0,0]
	v_sub_f32_e32 v92, v100, v112
	v_sub_f32_e32 v94, v88, v110
	v_mov_b32_e32 v98, v106
	v_mov_b32_e32 v99, v108
	v_mov_b32_e32 v100, v102
	v_mov_b32_e32 v101, v104

; __device__ __forceinline__ unsigned pkbf(float lo, float hi) { return pg8::cvt_pk_bf16(lo, hi); }
;     __device__ __forceinline__ void operator()(const f32x4 (&acc)[2][2][4][2], const Unit& u, int wr, int wc, int fr, int fq) const {
;     ...
;                     const int row = pm * 256 + ai * 128 + wr * 64 + m * 16 + fr;
;                     const float rinv = rsqrtf(rowsq[row] * (1.f / DM) + EPSN);
;                     int b, kidx, t = 0;
;                     if (isctx) { const int rc = row - MLAT; b = rc >> 8; kidx = rc & 255; } else { b = row >> 13; t = row & (SEQ - 1); kidx = CTXL + t; }
;                     f32x4 val[2][2]; float ss = 0.f;
; #pragma unroll
;                     for (int bj = 0; bj < 2; ++bj)
; #pragma unroll
;                         for (int n = 0; n < 2; ++n) { val[bj][n] = acc[ai][bj][m][n] * rinv + bv[bj][n]; const f32x4 q = val[bj][n]; ss += (q[0] * q[0] + q[1] * q[1]) + (q[2] * q[2] + q[3] * q[3]); }
;                     ss += __shfl_xor(ss, 16); ss += __shfl_xor(ss, 32);
;                     const float rn = rsqrtf(ss * (1.f / 64.f) + EPSN);
; #pragma unroll
;                     for (int bj = 0; bj < 2; ++bj) {
;                         f32x4 y0 = val[bj][0] * rn * gv[bj][0], y1 = val[bj][1] * rn * gv[bj][1];
;                         if (!isctx) {
;                             const int pos = bj == 0 ? (t >> 6) : (t & 63);
;                             const f32x4 r0 = *(const f32x4*)(rope + (size_t)(pos * 16 + 4 * fq) * 2);
;                             const f32x4 r1 = *(const f32x4*)(rope + (size_t)(pos * 16 + 4 * fq + 2) * 2);
;                             f32x4 z0, z1;
;                             z0[0] = y0[0] * r0[0] - y0[1] * r0[1]; z0[1] = y0[0] * r0[1] + y0[1] * r0[0];
;                             z0[2] = y0[2] * r0[2] - y0[3] * r0[3]; z0[3] = y0[2] * r0[3] + y0[3] * r0[2];
;                             z1[0] = y1[0] * r1[0] - y1[1] * r1[1]; z1[1] = y1[0] * r1[1] + y1[1] * r1[0];
;                             z1[2] = y1[2] * r1[2] - y1[3] * r1[3]; z1[3] = y1[2] * r1[3] + y1[3] * r1[2];
;                             y0 = z0; y1 = z1;
;                         }
;                         y0 = y0 * osc; y1 = y1 * osc;
;                         u32x4 w; w.x = pkbf(y0[0], y0[1]); w.y = pkbf(y0[2], y0[3]); w.z = pkbf(y1[0], y1[1]); w.w = pkbf(y1[2], y1[3]);
.LBB0_243:
	v_mov_b32_e32 v84, v128
	v_mov_b32_e32 v85, v128
	v_pk_mul_f32 v[86:87], v[128:129], v[86:87]
	v_mov_b32_e32 v131, v177
	v_pk_mul_f32 v[90:91], v[84:85], v[92:93]
	v_pk_mul_f32 v[92:93], v[84:85], v[82:83]
	v_pk_mul_f32 v[82:83], v[128:129], v[80:81]
	v_cvt_pk_bf16_f32 v80, v86, v87
	v_lshl_add_u64 v[86:87], v[88:89], 0, v[130:131]
	s_add_i32 s56, s25, 0x80
	v_cvt_pk_bf16_f32 v81, v90, v91
	v_cvt_pk_bf16_f32 v82, v82, v83
	v_cvt_pk_bf16_f32 v83, v92, v93
	flat_store_dwordx4 v[86:87], v[80:83]
	s_nop 1
	v_or_b32_e32 v80, s56, v171
	v_ashrrev_i32_e32 v81, 31, v80
	v_lshl_add_u64 v[82:83], v[80:81], 2, s[16:17]
	s_nop 1
	v_fmamk_f32 v81, v217, 0x3a800000, v224
	v_cmp_gt_f32_e32 vcc, s33, v81
	v_mul_f32_e32 v86, 0x4b800000, v81
	s_nop 0
	v_cndmask_b32_e32 v81, v81, v86, vcc
	v_rsq_f32_e32 v81, v81
	s_nop 0
	v_mul_f32_e32 v86, 0x45800000, v81
	v_cndmask_b32_e32 v86, v81, v86, vcc
	v_pk_fma_f32 v[76:77], v[76:77], v[86:87], v[44:45] op_sel_hi:[1,0,1]
	v_pk_fma_f32 v[78:79], v[78:79], v[86:87], v[46:47] op_sel_hi:[1,0,1]
	v_pk_mul_f32 v[90:91], v[76:77], v[76:77]
	v_pk_mul_f32 v[88:89], v[78:79], v[78:79]
	v_pk_fma_f32 v[74:75], v[74:75], v[86:87], v[42:43] op_sel_hi:[1,0,1]
	v_pk_mov_b32 v[92:93], v[90:91], v[88:89] op_sel:[1,0]
	v_mov_b32_e32 v91, v89
	v_pk_add_f32 v[88:89], v[92:93], v[90:91]
	v_pk_fma_f32 v[90:91], v[72:73], v[86:87], v[40:41] op_sel_hi:[1,0,1]
	v_pk_mul_f32 v[72:73], v[74:75], v[74:75]
	v_pk_mul_f32 v[92:93], v[90:91], v[90:91]
	v_pk_fma_f32 v[68:69], v[68:69], v[86:87], v[36:37] op_sel_hi:[1,0,1]
	v_pk_mov_b32 v[94:95], v[92:93], v[72:73] op_sel:[1,0]
	v_mov_b32_e32 v93, v73
	v_pk_add_f32 v[72:73], v[94:95], v[92:93]
	v_pk_fma_f32 v[70:71], v[70:71], v[86:87], v[38:39] op_sel_hi:[1,0,1]
	v_pk_add_f32 v[72:73], v[72:73], v[72:73] op_sel_hi:[0,1]
	v_mul_f32_e32 v72, v68, v68
	v_pk_fma_f32 v[92:93], v[68:69], v[68:69], v[72:73] op_sel_hi:[1,1,0]
	v_mul_f32_e32 v72, v70, v70
	v_pk_add_f32 v[88:89], v[88:89], v[88:89] op_sel_hi:[0,1]
	v_pk_fma_f32 v[94:95], v[70:71], v[70:71], v[72:73] op_sel_hi:[1,1,0]
	v_pk_fma_f32 v[66:67], v[66:67], v[86:87], v[34:35] op_sel_hi:[1,0,1]
	v_pk_fma_f32 v[64:65], v[64:65], v[86:87], v[32:33] op_sel_hi:[1,0,1]
	v_mul_f32_e32 v88, v66, v66
	v_mul_f32_e32 v92, v64, v64
	v_mul_f32_e32 v94, v65, v65
	v_mul_f32_e32 v72, v67, v67
	v_pk_add_f32 v[86:87], v[92:93], v[94:95]
	v_pk_add_f32 v[72:73], v[88:89], v[72:73]
	s_nop 0
	v_pk_add_f32 v[72:73], v[86:87], v[72:73]
	s_nop 0
	v_add_f32_e32 v72, v72, v73
	ds_bpermute_b32 v73, v201, v72
	s_waitcnt lgkmcnt(0)
	v_add_f32_e32 v72, v72, v73
	ds_bpermute_b32 v73, v202, v72
	s_waitcnt lgkmcnt(0)
	v_add_f32_e32 v72, v72, v73
	v_fmamk_f32 v72, v72, 0x3c800000, v224
	v_cmp_gt_f32_e32 vcc, s33, v72
	v_mul_f32_e32 v73, 0x4b800000, v72
	s_nop 0
	v_cndmask_b32_e32 v72, v72, v73, vcc
	v_rsq_f32_e32 v72, v72
	s_nop 0
	v_mul_f32_e32 v73, 0x45800000, v72
	v_cndmask_b32_e32 v72, v72, v73, vcc
	v_pk_mul_f32 v[76:77], v[76:77], v[72:73] op_sel_hi:[1,0]
	v_pk_mul_f32 v[78:79], v[78:79], v[72:73] op_sel_hi:[1,0]
	v_pk_mul_f32 v[86:87], v[90:91], v[72:73] op_sel_hi:[1,0]
	v_pk_mul_f32 v[74:75], v[74:75], v[72:73] op_sel_hi:[1,0]
	v_pk_mul_f32 v[88:89], v[158:159], v[78:79]
	v_pk_mul_f32 v[76:77], v[156:157], v[76:77]
	v_pk_mul_f32 v[78:79], v[154:155], v[74:75]
	v_pk_mul_f32 v[74:75], v[152:153], v[86:87]
	s_and_b64 vcc, exec, s[6:7]
	s_cbranch_vccnz .LBB0_245
	s_lshr_b32 s0, s56, 1
	s_and_b32 s0, s0, 0xfe0
	v_or_b32_e32 v73, s0, v168
	v_lshlrev_b32_e32 v86, 2, v73
	v_mov_b32_e32 v87, v177
	v_lshl_add_u64 v[86:87], s[18:19], 0, v[86:87]
	flat_load_dwordx4 v[90:93], v[86:87]
	flat_load_dwordx4 v[94:97], v[86:87] offset:16
	s_waitcnt vmcnt(0) lgkmcnt(0)
	v_pk_mul_f32 v[98:99], v[76:77], v[90:91] op_sel:[1,1] op_sel_hi:[1,0]
	v_pk_mul_f32 v[86:87], v[76:77], v[90:91]
	v_pk_fma_f32 v[76:77], v[76:77], v[90:91], v[98:99] op_sel_hi:[0,1,1]
	v_mul_f32_e32 v76, v89, v93
	v_pk_fma_f32 v[90:91], v[88:89], v[92:93], v[76:77] op_sel_hi:[1,1,0] neg_lo:[0,0,1] neg_hi:[0,0,1]
	v_mul_f32_e32 v76, v89, v92
	v_pk_mul_f32 v[100:101], v[74:75], v[94:95] op_sel:[1,1] op_sel_hi:[1,0]
	v_pk_fma_f32 v[92:93], v[88:89], v[92:93], v[76:77] op_sel:[0,1,0] op_sel_hi:[1,0,0]
	v_pk_mul_f32 v[88:89], v[74:75], v[94:95]
	v_pk_fma_f32 v[74:75], v[74:75], v[94:95], v[100:101] op_sel_hi:[0,1,1]
	v_mul_f32_e32 v74, v79, v97
	v_pk_fma_f32 v[94:95], v[78:79], v[96:97], v[74:75] op_sel_hi:[1,1,0] neg_lo:[0,0,1] neg_hi:[0,0,1]
	v_mul_f32_e32 v74, v79, v96
	v_pk_fma_f32 v[96:97], v[78:79], v[96:97], v[74:75] op_sel:[0,1,0] op_sel_hi:[1,0,0]
	v_sub_f32_e32 v74, v88, v100
	v_sub_f32_e32 v76, v86, v98
	v_mov_b32_e32 v78, v94
	v_mov_b32_e32 v79, v96
	v_mov_b32_e32 v88, v90
	v_mov_b32_e32 v89, v92

;     __device__ __forceinline__ void operator()(const f32x4 (&acc)[2][2][4][2], const Unit& u, int wr, int wc, int fr, int fq) const {
;     ...
;                     const float rinv = rsqrtf(rowsq[row] * (1.f / DM) + EPSN);
;                     int b, kidx, t = 0;
;                     if (isctx) { const int rc = row - MLAT; b = rc >> 8; kidx = rc & 255; } else { b = row >> 13; t = row & (SEQ - 1); kidx = CTXL + t; }
;                     f32x4 val[2][2]; float ss = 0.f;
; #pragma unroll
;                     for (int bj = 0; bj < 2; ++bj)
; #pragma unroll
;                         for (int n = 0; n < 2; ++n) { val[bj][n] = acc[ai][bj][m][n] * rinv + bv[bj][n]; const f32x4 q = val[bj][n]; ss += (q[0] * q[0] + q[1] * q[1]) + (q[2] * q[2] + q[3] * q[3]); }
;                     ss += __shfl_xor(ss, 16); ss += __shfl_xor(ss, 32);
;                     const float rn = rsqrtf(ss * (1.f / 64.f) + EPSN);
; #pragma unroll
;                     for (int bj = 0; bj < 2; ++bj) {
;                         f32x4 y0 = val[bj][0] * rn * gv[bj][0], y1 = val[bj][1] * rn * gv[bj][1];
;                         if (!isctx) {
;                             const int pos = bj == 0 ? (t >> 6) : (t & 63);
;                             const f32x4 r0 = *(const f32x4*)(rope + (size_t)(pos * 16 + 4 * fq) * 2);
;                             const f32x4 r1 = *(const f32x4*)(rope + (size_t)(pos * 16 + 4 * fq + 2) * 2);
;                             f32x4 z0, z1;
;                             z0[0] = y0[0] * r0[0] - y0[1] * r0[1]; z0[1] = y0[0] * r0[1] + y0[1] * r0[0];
;                             z0[2] = y0[2] * r0[2] - y0[3] * r0[3]; z0[3] = y0[2] * r0[3] + y0[3] * r0[2];
;                             z1[0] = y1[0] * r1[0] - y1[1] * r1[1]; z1[1] = y1[0] * r1[1] + y1[1] * r1[0];
;                             z1[2] = y1[2] * r1[2] - y1[3] * r1[3]; z1[3] = y1[2] * r1[3] + y1[3] * r1[2];
;                             y0 = z0; y1 = z1;
;                         }
;                         y0 = y0 * osc; y1 = y1 * osc;
;                         u32x4 w; w.x = pkbf(y0[0], y0[1]); w.y = pkbf(y0[2], y0[3]); w.z = pkbf(y1[0], y1[1]); w.w = pkbf(y1[2], y1[3]);
;                         const size_t off = (size_t)(b * 8 + hc) * (LK * 64) + (size_t)(kidx >> 6) * 4096 + (size_t)(4 * bj + fq) * 512 + (size_t)(kidx & 63) * 8;
;                         *(u32x4*)(dst + off) = w;
.LBB0_247:
	v_mov_b32_e32 v64, v128
	v_mov_b32_e32 v65, v128
	v_pk_mul_f32 v[68:69], v[128:129], v[68:69]
	v_pk_mul_f32 v[70:71], v[64:65], v[70:71]
	v_mov_b32_e32 v131, v177
	v_pk_mul_f32 v[72:73], v[64:65], v[74:75]
	v_pk_mul_f32 v[74:75], v[128:129], v[66:67]
	v_cvt_pk_bf16_f32 v66, v68, v69
	v_cvt_pk_bf16_f32 v67, v72, v73
	s_nop 0
	v_cvt_pk_bf16_f32 v68, v74, v75
	v_cvt_pk_bf16_f32 v69, v70, v71
	v_lshl_add_u64 v[70:71], v[86:87], 0, v[130:131]
	flat_store_dwordx4 v[70:71], v[66:69]
	s_nop 1
	v_fmamk_f32 v66, v218, 0x3a800000, v224
	v_mul_f32_e32 v67, 0x4b800000, v66
	v_cmp_gt_f32_e32 vcc, s33, v66
	s_nop 1
	v_cndmask_b32_e32 v66, v66, v67, vcc
	v_rsq_f32_e32 v66, v66
	s_nop 0
	v_mul_f32_e32 v67, 0x45800000, v66
	v_cndmask_b32_e32 v66, v66, v67, vcc
	v_pk_fma_f32 v[60:61], v[60:61], v[66:67], v[44:45] op_sel_hi:[1,0,1]
	v_pk_fma_f32 v[62:63], v[62:63], v[66:67], v[46:47] op_sel_hi:[1,0,1]
	v_pk_fma_f32 v[56:57], v[56:57], v[66:67], v[40:41] op_sel_hi:[1,0,1]
	v_pk_fma_f32 v[68:69], v[58:59], v[66:67], v[42:43] op_sel_hi:[1,0,1]
	v_pk_fma_f32 v[54:55], v[54:55], v[66:67], v[38:39] op_sel_hi:[1,0,1]
	v_pk_fma_f32 v[52:53], v[52:53], v[66:67], v[36:37] op_sel_hi:[1,0,1]
	v_pk_fma_f32 v[50:51], v[50:51], v[66:67], v[34:35] op_sel_hi:[1,0,1]
	v_pk_fma_f32 v[48:49], v[48:49], v[66:67], v[32:33] op_sel_hi:[1,0,1]
	v_pk_mul_f32 v[58:59], v[62:63], v[62:63]
	v_pk_mul_f32 v[66:67], v[60:61], v[60:61]
	v_pk_mul_f32 v[70:71], v[68:69], v[68:69]
	v_pk_mul_f32 v[72:73], v[56:57], v[56:57]
	v_pk_mov_b32 v[78:79], v[66:67], v[58:59] op_sel:[1,0]
	v_mov_b32_e32 v67, v59
	v_pk_mov_b32 v[58:59], v[72:73], v[70:71] op_sel:[1,0]
	v_mov_b32_e32 v73, v71
	v_mul_f32_e32 v74, v52, v52
	v_mul_f32_e32 v76, v54, v54
	v_pk_add_f32 v[66:67], v[78:79], v[66:67]
	v_pk_add_f32 v[58:59], v[58:59], v[72:73]
	v_pk_fma_f32 v[70:71], v[52:53], v[52:53], v[74:75] op_sel_hi:[1,1,0]
	v_pk_fma_f32 v[74:75], v[54:55], v[54:55], v[76:77] op_sel_hi:[1,1,0]
	v_pk_add_f32 v[66:67], v[66:67], v[66:67] op_sel_hi:[0,1]
	v_pk_add_f32 v[58:59], v[58:59], v[58:59] op_sel_hi:[0,1]
	v_mul_f32_e32 v70, v48, v48
	v_mul_f32_e32 v74, v49, v49
	v_mul_f32_e32 v66, v50, v50
	v_mul_f32_e32 v58, v51, v51
	v_pk_add_f32 v[70:71], v[70:71], v[74:75]
	v_pk_add_f32 v[58:59], v[66:67], v[58:59]
	s_and_b64 vcc, exec, s[6:7]
	v_pk_add_f32 v[58:59], v[70:71], v[58:59]
	s_nop 0
	v_add_f32_e32 v58, v58, v59
	ds_bpermute_b32 v59, v201, v58
	s_waitcnt lgkmcnt(0)
	v_add_f32_e32 v58, v58, v59
	ds_bpermute_b32 v59, v202, v58
	s_waitcnt lgkmcnt(0)
	v_add_f32_e32 v58, v58, v59
	v_fmamk_f32 v58, v58, 0x3c800000, v224
	v_mul_f32_e32 v59, 0x4b800000, v58
	v_cmp_gt_f32_e64 s[0:1], s33, v58
	s_nop 1
	v_cndmask_b32_e64 v58, v58, v59, s[0:1]
	v_rsq_f32_e32 v58, v58
	s_nop 0
	v_mul_f32_e32 v59, 0x45800000, v58
	v_cndmask_b32_e64 v58, v58, v59, s[0:1]
	v_pk_mul_f32 v[60:61], v[60:61], v[58:59] op_sel_hi:[1,0]
	v_pk_mul_f32 v[62:63], v[62:63], v[58:59] op_sel_hi:[1,0]
	v_pk_mul_f32 v[56:57], v[56:57], v[58:59] op_sel_hi:[1,0]
	v_pk_mul_f32 v[66:67], v[68:69], v[58:59] op_sel_hi:[1,0]
	v_pk_mul_f32 v[68:69], v[158:159], v[62:63]
	v_pk_mul_f32 v[62:63], v[156:157], v[60:61]
	v_pk_mul_f32 v[66:67], v[154:155], v[66:67]
	v_pk_mul_f32 v[60:61], v[152:153], v[56:57]
	s_cbranch_vccnz .LBB0_249
	s_lshr_b32 s0, s56, 1
	s_and_b32 s0, s0, 0xfe0
	v_or_b32_e32 v56, s0, v168
	v_lshlrev_b32_e32 v56, 2, v56
	v_mov_b32_e32 v57, v177
	v_lshl_add_u64 v[56:57], s[18:19], 0, v[56:57]
	flat_load_dwordx4 v[70:73], v[56:57]
	flat_load_dwordx4 v[74:77], v[56:57] offset:16
	s_waitcnt vmcnt(0) lgkmcnt(0)
	v_pk_mul_f32 v[78:79], v[62:63], v[70:71] op_sel:[1,1] op_sel_hi:[1,0]
	v_pk_mul_f32 v[56:57], v[62:63], v[70:71]
	v_pk_fma_f32 v[62:63], v[62:63], v[70:71], v[78:79] op_sel_hi:[0,1,1]
	v_mul_f32_e32 v62, v69, v73
	v_pk_fma_f32 v[70:71], v[68:69], v[72:73], v[62:63] op_sel_hi:[1,1,0] neg_lo:[0,0,1] neg_hi:[0,0,1]
	v_mul_f32_e32 v62, v69, v72
	v_pk_mul_f32 v[84:85], v[60:61], v[74:75] op_sel:[1,1] op_sel_hi:[1,0]
	v_pk_fma_f32 v[72:73], v[68:69], v[72:73], v[62:63] op_sel:[0,1,0] op_sel_hi:[1,0,0]
	v_pk_mul_f32 v[68:69], v[60:61], v[74:75]
	v_pk_fma_f32 v[60:61], v[60:61], v[74:75], v[84:85] op_sel_hi:[0,1,1]
	v_mul_f32_e32 v60, v67, v77
	v_pk_fma_f32 v[74:75], v[66:67], v[76:77], v[60:61] op_sel_hi:[1,1,0] neg_lo:[0,0,1] neg_hi:[0,0,1]
	v_mul_f32_e32 v60, v67, v76
	v_pk_fma_f32 v[76:77], v[66:67], v[76:77], v[60:61] op_sel:[0,1,0] op_sel_hi:[1,0,0]
	v_sub_f32_e32 v60, v68, v84
	v_sub_f32_e32 v62, v56, v78
	v_mov_b32_e32 v66, v74
	v_mov_b32_e32 v67, v76
	v_mov_b32_e32 v68, v70
	v_mov_b32_e32 v69, v72

;     __device__ __forceinline__ void operator()(const f32x4 (&acc)[2][2][4][2], const Unit& u, int wr, int wc, int fr, int fq) const {
;     ...
;                     const float rinv = rsqrtf(rowsq[row] * (1.f / DM) + EPSN);
;                     int b, kidx, t = 0;
;                     if (isctx) { const int rc = row - MLAT; b = rc >> 8; kidx = rc & 255; } else { b = row >> 13; t = row & (SEQ - 1); kidx = CTXL + t; }
;                     f32x4 val[2][2]; float ss = 0.f;
; #pragma unroll
;                     for (int bj = 0; bj < 2; ++bj)
; #pragma unroll
;                         for (int n = 0; n < 2; ++n) { val[bj][n] = acc[ai][bj][m][n] * rinv + bv[bj][n]; const f32x4 q = val[bj][n]; ss += (q[0] * q[0] + q[1] * q[1]) + (q[2] * q[2] + q[3] * q[3]); }
;                     ss += __shfl_xor(ss, 16); ss += __shfl_xor(ss, 32);
;                     const float rn = rsqrtf(ss * (1.f / 64.f) + EPSN);
; #pragma unroll
;                     for (int bj = 0; bj < 2; ++bj) {
;                         f32x4 y0 = val[bj][0] * rn * gv[bj][0], y1 = val[bj][1] * rn * gv[bj][1];
;                         if (!isctx) {
;                             const int pos = bj == 0 ? (t >> 6) : (t & 63);
;                             const f32x4 r0 = *(const f32x4*)(rope + (size_t)(pos * 16 + 4 * fq) * 2);
;                             const f32x4 r1 = *(const f32x4*)(rope + (size_t)(pos * 16 + 4 * fq + 2) * 2);
;                             f32x4 z0, z1;
;                             z0[0] = y0[0] * r0[0] - y0[1] * r0[1]; z0[1] = y0[0] * r0[1] + y0[1] * r0[0];
;                             z0[2] = y0[2] * r0[2] - y0[3] * r0[3]; z0[3] = y0[2] * r0[3] + y0[3] * r0[2];
;                             z1[0] = y1[0] * r1[0] - y1[1] * r1[1]; z1[1] = y1[0] * r1[1] + y1[1] * r1[0];
;                             z1[2] = y1[2] * r1[2] - y1[3] * r1[3]; z1[3] = y1[2] * r1[3] + y1[3] * r1[2];
;                             y0 = z0; y1 = z1;
;                         }
;                         y0 = y0 * osc; y1 = y1 * osc;
;                         u32x4 w; w.x = pkbf(y0[0], y0[1]); w.y = pkbf(y0[2], y0[3]); w.z = pkbf(y1[0], y1[1]); w.w = pkbf(y1[2], y1[3]);
;                         const size_t off = (size_t)(b * 8 + hc) * (LK * 64) + (size_t)(kidx >> 6) * 4096 + (size_t)(4 * bj + fq) * 512 + (size_t)(kidx & 63) * 8;
;                         *(u32x4*)(dst + off) = w;
.LBB0_251:
	v_mov_b32_e32 v48, v128
	v_mov_b32_e32 v49, v128
	v_pk_mul_f32 v[52:53], v[128:129], v[52:53]
	v_pk_mul_f32 v[54:55], v[48:49], v[54:55]
	v_mov_b32_e32 v131, v177
	v_pk_mul_f32 v[58:59], v[48:49], v[60:61]
	v_pk_mul_f32 v[60:61], v[128:129], v[50:51]
	v_cvt_pk_bf16_f32 v50, v52, v53
	v_cvt_pk_bf16_f32 v51, v58, v59
	s_nop 0
	v_cvt_pk_bf16_f32 v52, v60, v61
	v_cvt_pk_bf16_f32 v53, v54, v55
	v_lshl_add_u64 v[54:55], v[56:57], 0, v[130:131]
	flat_store_dwordx4 v[54:55], v[50:53]
	s_nop 1
	v_fmamk_f32 v50, v219, 0x3a800000, v224
	v_mul_f32_e32 v51, 0x4b800000, v50
	v_cmp_gt_f32_e32 vcc, s33, v50
	s_nop 1
	v_cndmask_b32_e32 v50, v50, v51, vcc
	v_rsq_f32_e32 v50, v50
	s_nop 0
	v_mul_f32_e32 v51, 0x45800000, v50
	v_cndmask_b32_e32 v50, v50, v51, vcc
	v_pk_fma_f32 v[28:29], v[28:29], v[50:51], v[44:45] op_sel_hi:[1,0,1]
	v_pk_fma_f32 v[30:31], v[30:31], v[50:51], v[46:47] op_sel_hi:[1,0,1]
	v_pk_fma_f32 v[24:25], v[24:25], v[50:51], v[40:41] op_sel_hi:[1,0,1]
	v_pk_fma_f32 v[52:53], v[26:27], v[50:51], v[42:43] op_sel_hi:[1,0,1]
	v_pk_fma_f32 v[22:23], v[22:23], v[50:51], v[38:39] op_sel_hi:[1,0,1]
	v_pk_fma_f32 v[20:21], v[20:21], v[50:51], v[36:37] op_sel_hi:[1,0,1]
	v_pk_fma_f32 v[18:19], v[18:19], v[50:51], v[34:35] op_sel_hi:[1,0,1]
	v_pk_fma_f32 v[16:17], v[16:17], v[50:51], v[32:33] op_sel_hi:[1,0,1]
	v_pk_mul_f32 v[26:27], v[30:31], v[30:31]
	v_pk_mul_f32 v[50:51], v[28:29], v[28:29]
	v_pk_mul_f32 v[54:55], v[52:53], v[52:53]
	v_pk_mul_f32 v[56:57], v[24:25], v[24:25]
	v_pk_mov_b32 v[62:63], v[50:51], v[26:27] op_sel:[1,0]
	v_mov_b32_e32 v51, v27
	v_pk_mov_b32 v[26:27], v[56:57], v[54:55] op_sel:[1,0]
	v_mov_b32_e32 v57, v55
	v_mul_f32_e32 v58, v20, v20
	v_mul_f32_e32 v60, v22, v22
	v_pk_add_f32 v[50:51], v[62:63], v[50:51]
	v_pk_add_f32 v[26:27], v[26:27], v[56:57]
	v_pk_fma_f32 v[54:55], v[20:21], v[20:21], v[58:59] op_sel_hi:[1,1,0]
	v_pk_fma_f32 v[58:59], v[22:23], v[22:23], v[60:61] op_sel_hi:[1,1,0]
	v_pk_add_f32 v[50:51], v[50:51], v[50:51] op_sel_hi:[0,1]
	v_pk_add_f32 v[26:27], v[26:27], v[26:27] op_sel_hi:[0,1]
	v_mul_f32_e32 v54, v16, v16
	v_mul_f32_e32 v58, v17, v17
	v_mul_f32_e32 v50, v18, v18
	v_mul_f32_e32 v26, v19, v19
	v_pk_add_f32 v[54:55], v[54:55], v[58:59]
	v_pk_add_f32 v[26:27], v[50:51], v[26:27]
	s_and_b64 vcc, exec, s[6:7]
	v_pk_add_f32 v[26:27], v[54:55], v[26:27]
	s_nop 0
	v_add_f32_e32 v26, v26, v27
	ds_bpermute_b32 v27, v201, v26
	s_waitcnt lgkmcnt(0)
	v_add_f32_e32 v26, v26, v27
	ds_bpermute_b32 v27, v202, v26
	s_waitcnt lgkmcnt(0)
	v_add_f32_e32 v26, v26, v27
	v_fmamk_f32 v26, v26, 0x3c800000, v224
	v_mul_f32_e32 v27, 0x4b800000, v26
	v_cmp_gt_f32_e64 s[0:1], s33, v26
	s_nop 1
	v_cndmask_b32_e64 v26, v26, v27, s[0:1]
	v_rsq_f32_e32 v26, v26
	s_nop 0
	v_mul_f32_e32 v27, 0x45800000, v26
	v_cndmask_b32_e64 v26, v26, v27, s[0:1]
	v_pk_mul_f32 v[28:29], v[28:29], v[26:27] op_sel_hi:[1,0]
	v_pk_mul_f32 v[30:31], v[30:31], v[26:27] op_sel_hi:[1,0]
	v_pk_mul_f32 v[24:25], v[24:25], v[26:27] op_sel_hi:[1,0]
	v_pk_mul_f32 v[50:51], v[52:53], v[26:27] op_sel_hi:[1,0]
	v_pk_mul_f32 v[52:53], v[158:159], v[30:31]
	v_pk_mul_f32 v[30:31], v[156:157], v[28:29]
	v_pk_mul_f32 v[50:51], v[154:155], v[50:51]
	v_pk_mul_f32 v[28:29], v[152:153], v[24:25]
	s_cbranch_vccnz .LBB0_253
	s_lshr_b32 s0, s56, 1
	s_and_b32 s0, s0, 0xfe0
	v_or_b32_e32 v24, s0, v168
	v_lshlrev_b32_e32 v24, 2, v24
	v_mov_b32_e32 v25, v177
	v_lshl_add_u64 v[24:25], s[18:19], 0, v[24:25]
	flat_load_dwordx4 v[54:57], v[24:25]
	flat_load_dwordx4 v[58:61], v[24:25] offset:16
	s_waitcnt vmcnt(0) lgkmcnt(0)
	v_pk_mul_f32 v[62:63], v[30:31], v[54:55] op_sel:[1,1] op_sel_hi:[1,0]
	v_pk_mul_f32 v[24:25], v[30:31], v[54:55]
	v_pk_fma_f32 v[30:31], v[30:31], v[54:55], v[62:63] op_sel_hi:[0,1,1]
	v_mul_f32_e32 v30, v53, v57
	v_pk_fma_f32 v[54:55], v[52:53], v[56:57], v[30:31] op_sel_hi:[1,1,0] neg_lo:[0,0,1] neg_hi:[0,0,1]
	v_mul_f32_e32 v30, v53, v56
	v_pk_mul_f32 v[64:65], v[28:29], v[58:59] op_sel:[1,1] op_sel_hi:[1,0]
	v_pk_fma_f32 v[56:57], v[52:53], v[56:57], v[30:31] op_sel:[0,1,0] op_sel_hi:[1,0,0]
	v_pk_mul_f32 v[52:53], v[28:29], v[58:59]
	v_pk_fma_f32 v[28:29], v[28:29], v[58:59], v[64:65] op_sel_hi:[0,1,1]
	v_mul_f32_e32 v28, v51, v61
	v_pk_fma_f32 v[58:59], v[50:51], v[60:61], v[28:29] op_sel_hi:[1,1,0] neg_lo:[0,0,1] neg_hi:[0,0,1]
	v_mul_f32_e32 v28, v51, v60
	v_pk_fma_f32 v[60:61], v[50:51], v[60:61], v[28:29] op_sel:[0,1,0] op_sel_hi:[1,0,0]
	v_sub_f32_e32 v28, v52, v64
	v_sub_f32_e32 v30, v24, v62
	v_mov_b32_e32 v50, v58
	v_mov_b32_e32 v51, v60
	v_mov_b32_e32 v52, v54
	v_mov_b32_e32 v53, v56

;     __device__ __forceinline__ void operator()(const f32x4 (&acc)[2][2][4][2], const Unit& u, int wr, int wc, int fr, int fq) const {
;     ...
;                     const float rinv = rsqrtf(rowsq[row] * (1.f / DM) + EPSN);
;                     int b, kidx, t = 0;
;                     if (isctx) { const int rc = row - MLAT; b = rc >> 8; kidx = rc & 255; } else { b = row >> 13; t = row & (SEQ - 1); kidx = CTXL + t; }
;                     f32x4 val[2][2]; float ss = 0.f;
; #pragma unroll
;                     for (int bj = 0; bj < 2; ++bj)
; #pragma unroll
;                         for (int n = 0; n < 2; ++n) { val[bj][n] = acc[ai][bj][m][n] * rinv + bv[bj][n]; const f32x4 q = val[bj][n]; ss += (q[0] * q[0] + q[1] * q[1]) + (q[2] * q[2] + q[3] * q[3]); }
;                     ss += __shfl_xor(ss, 16); ss += __shfl_xor(ss, 32);
;                     const float rn = rsqrtf(ss * (1.f / 64.f) + EPSN);
; #pragma unroll
;                     for (int bj = 0; bj < 2; ++bj) {
;                         f32x4 y0 = val[bj][0] * rn * gv[bj][0], y1 = val[bj][1] * rn * gv[bj][1];
;                         if (!isctx) {
;                             const int pos = bj == 0 ? (t >> 6) : (t & 63);
;                             const f32x4 r0 = *(const f32x4*)(rope + (size_t)(pos * 16 + 4 * fq) * 2);
;                             const f32x4 r1 = *(const f32x4*)(rope + (size_t)(pos * 16 + 4 * fq + 2) * 2);
;                             f32x4 z0, z1;
;                             z0[0] = y0[0] * r0[0] - y0[1] * r0[1]; z0[1] = y0[0] * r0[1] + y0[1] * r0[0];
;                             z0[2] = y0[2] * r0[2] - y0[3] * r0[3]; z0[3] = y0[2] * r0[3] + y0[3] * r0[2];
;                             z1[0] = y1[0] * r1[0] - y1[1] * r1[1]; z1[1] = y1[0] * r1[1] + y1[1] * r1[0];
;                             z1[2] = y1[2] * r1[2] - y1[3] * r1[3]; z1[3] = y1[2] * r1[3] + y1[3] * r1[2];
;                             y0 = z0; y1 = z1;
;                         }
;                         y0 = y0 * osc; y1 = y1 * osc;
;                         u32x4 w; w.x = pkbf(y0[0], y0[1]); w.y = pkbf(y0[2], y0[3]); w.z = pkbf(y1[0], y1[1]); w.w = pkbf(y1[2], y1[3]);
;                         const size_t off = (size_t)(b * 8 + hc) * (LK * 64) + (size_t)(kidx >> 6) * 4096 + (size_t)(4 * bj + fq) * 512 + (size_t)(kidx & 63) * 8;
;                         *(u32x4*)(dst + off) = w;
.LBB0_255:
	v_mov_b32_e32 v16, v128
	v_mov_b32_e32 v17, v128
	v_pk_mul_f32 v[20:21], v[128:129], v[20:21]
	v_pk_mul_f32 v[22:23], v[16:17], v[22:23]
	v_mov_b32_e32 v131, v177
	v_pk_mul_f32 v[26:27], v[16:17], v[28:29]
	v_pk_mul_f32 v[28:29], v[128:129], v[18:19]
	v_cvt_pk_bf16_f32 v18, v20, v21
	v_cvt_pk_bf16_f32 v19, v26, v27
	s_nop 0
	v_cvt_pk_bf16_f32 v20, v28, v29
	v_cvt_pk_bf16_f32 v21, v22, v23
	v_lshl_add_u64 v[22:23], v[24:25], 0, v[130:131]
	flat_store_dwordx4 v[22:23], v[18:21]
	s_nop 1
	v_fmamk_f32 v18, v220, 0x3a800000, v224
	v_mul_f32_e32 v19, 0x4b800000, v18
	v_cmp_gt_f32_e32 vcc, s33, v18
	s_nop 1
	v_cndmask_b32_e32 v18, v18, v19, vcc
	v_rsq_f32_e32 v18, v18
	s_nop 0
	v_mul_f32_e32 v19, 0x45800000, v18
	v_cndmask_b32_e32 v18, v18, v19, vcc
	v_pk_fma_f32 v[12:13], v[12:13], v[18:19], v[44:45] op_sel_hi:[1,0,1]
	v_pk_fma_f32 v[14:15], v[14:15], v[18:19], v[46:47] op_sel_hi:[1,0,1]
	v_pk_fma_f32 v[8:9], v[8:9], v[18:19], v[40:41] op_sel_hi:[1,0,1]
	v_pk_fma_f32 v[20:21], v[10:11], v[18:19], v[42:43] op_sel_hi:[1,0,1]
	v_pk_fma_f32 v[6:7], v[6:7], v[18:19], v[38:39] op_sel_hi:[1,0,1]
	v_pk_fma_f32 v[4:5], v[4:5], v[18:19], v[36:37] op_sel_hi:[1,0,1]
	v_pk_fma_f32 v[2:3], v[2:3], v[18:19], v[34:35] op_sel_hi:[1,0,1]
	v_pk_fma_f32 v[0:1], v[0:1], v[18:19], v[32:33] op_sel_hi:[1,0,1]
	v_pk_mul_f32 v[10:11], v[14:15], v[14:15]
	v_pk_mul_f32 v[18:19], v[12:13], v[12:13]
	v_pk_mul_f32 v[22:23], v[20:21], v[20:21]
	v_pk_mul_f32 v[24:25], v[8:9], v[8:9]
	v_pk_mov_b32 v[30:31], v[18:19], v[10:11] op_sel:[1,0]
	v_mov_b32_e32 v19, v11
	v_pk_mov_b32 v[10:11], v[24:25], v[22:23] op_sel:[1,0]
	v_mov_b32_e32 v25, v23
	v_mul_f32_e32 v26, v4, v4
	v_mul_f32_e32 v28, v6, v6
	v_pk_add_f32 v[18:19], v[30:31], v[18:19]
	v_pk_add_f32 v[10:11], v[10:11], v[24:25]
	v_pk_fma_f32 v[22:23], v[4:5], v[4:5], v[26:27] op_sel_hi:[1,1,0]
	v_pk_fma_f32 v[26:27], v[6:7], v[6:7], v[28:29] op_sel_hi:[1,1,0]
	v_pk_add_f32 v[18:19], v[18:19], v[18:19] op_sel_hi:[0,1]
	v_pk_add_f32 v[10:11], v[10:11], v[10:11] op_sel_hi:[0,1]
	v_mul_f32_e32 v22, v0, v0
	v_mul_f32_e32 v26, v1, v1
	v_mul_f32_e32 v18, v2, v2
	v_mul_f32_e32 v10, v3, v3
	v_pk_add_f32 v[22:23], v[22:23], v[26:27]
	v_pk_add_f32 v[10:11], v[18:19], v[10:11]
	s_and_b64 vcc, exec, s[6:7]
	v_pk_add_f32 v[10:11], v[22:23], v[10:11]
	s_nop 0
	v_add_f32_e32 v10, v10, v11
	ds_bpermute_b32 v11, v201, v10
	s_waitcnt lgkmcnt(0)
	v_add_f32_e32 v10, v10, v11
	ds_bpermute_b32 v11, v202, v10
	s_waitcnt lgkmcnt(0)
	v_add_f32_e32 v10, v10, v11
	v_fmamk_f32 v10, v10, 0x3c800000, v224
	v_mul_f32_e32 v11, 0x4b800000, v10
	v_cmp_gt_f32_e64 s[0:1], s33, v10
	s_nop 1
	v_cndmask_b32_e64 v10, v10, v11, s[0:1]
	v_rsq_f32_e32 v10, v10
	s_nop 0
	v_mul_f32_e32 v11, 0x45800000, v10
	v_cndmask_b32_e64 v10, v10, v11, s[0:1]
	v_pk_mul_f32 v[12:13], v[12:13], v[10:11] op_sel_hi:[1,0]
	v_pk_mul_f32 v[14:15], v[14:15], v[10:11] op_sel_hi:[1,0]
	v_pk_mul_f32 v[8:9], v[8:9], v[10:11] op_sel_hi:[1,0]
	v_pk_mul_f32 v[18:19], v[20:21], v[10:11] op_sel_hi:[1,0]
	v_pk_mul_f32 v[20:21], v[158:159], v[14:15]
	v_pk_mul_f32 v[14:15], v[156:157], v[12:13]
	v_pk_mul_f32 v[18:19], v[154:155], v[18:19]
	v_pk_mul_f32 v[12:13], v[152:153], v[8:9]
	s_cbranch_vccnz .LBB0_257
	s_lshr_b32 s0, s56, 1
	s_and_b32 s0, s0, 0xfe0
	v_or_b32_e32 v8, s0, v168
	v_lshlrev_b32_e32 v8, 2, v8
	v_mov_b32_e32 v9, v177
	v_lshl_add_u64 v[8:9], s[18:19], 0, v[8:9]
	flat_load_dwordx4 v[22:25], v[8:9]
	flat_load_dwordx4 v[26:29], v[8:9] offset:16
	s_waitcnt vmcnt(0) lgkmcnt(0)
	v_pk_mul_f32 v[30:31], v[14:15], v[22:23] op_sel:[1,1] op_sel_hi:[1,0]
	v_pk_mul_f32 v[8:9], v[14:15], v[22:23]
	v_pk_fma_f32 v[14:15], v[14:15], v[22:23], v[30:31] op_sel_hi:[0,1,1]
	v_mul_f32_e32 v14, v21, v25
	v_pk_fma_f32 v[22:23], v[20:21], v[24:25], v[14:15] op_sel_hi:[1,1,0] neg_lo:[0,0,1] neg_hi:[0,0,1]
	v_mul_f32_e32 v14, v21, v24
	v_pk_mul_f32 v[32:33], v[12:13], v[26:27] op_sel:[1,1] op_sel_hi:[1,0]
	v_pk_fma_f32 v[24:25], v[20:21], v[24:25], v[14:15] op_sel:[0,1,0] op_sel_hi:[1,0,0]
	v_pk_mul_f32 v[20:21], v[12:13], v[26:27]
	v_pk_fma_f32 v[12:13], v[12:13], v[26:27], v[32:33] op_sel_hi:[0,1,1]
	v_mul_f32_e32 v12, v19, v29
	v_pk_fma_f32 v[26:27], v[18:19], v[28:29], v[12:13] op_sel_hi:[1,1,0] neg_lo:[0,0,1] neg_hi:[0,0,1]
	v_mul_f32_e32 v12, v19, v28
	v_pk_fma_f32 v[28:29], v[18:19], v[28:29], v[12:13] op_sel:[0,1,0] op_sel_hi:[1,0,0]
	v_sub_f32_e32 v12, v20, v32
	v_sub_f32_e32 v14, v8, v30
	v_mov_b32_e32 v18, v26
	v_mov_b32_e32 v19, v28
	v_mov_b32_e32 v20, v22
	v_mov_b32_e32 v21, v24
